# S5 item prologue: the 8 serialized conditional B-fragment loads and 32-register tuple shuffles replaced by zero-fill plus 8 loads issued together into the fragment registers
# speedup vs baseline: 1.0118x; 1.0036x over previous
.LBB0_1271:
	s_andn2_b64 vcc, exec, s[0:1]
	s_cbranch_vccnz .LBB0_1317
	v_mov_b32_e32 v247, v234
	s_lshl_b32 s0, s3, 2
	s_addk_i32 s0, 0xf400
	v_ashrrev_i32_e32 v242, 6, v247
	v_add_u32_e32 v245, s0, v242
	s_movk_i32 s0, 0x100
	v_cmp_gt_i32_e64 s[4:5], s0, v245
	s_movk_i32 s0, 0xff
	v_cmp_lt_i32_e32 vcc, s0, v245
	s_and_saveexec_b64 s[0:1], vcc
	s_xor_b64 s[0:1], exec, s[0:1]
	v_add_u32_e32 v0, 0xffffff00, v245
	v_lshrrev_b32_e32 v246, 6, v0
	v_lshlrev_b32_e32 v240, 8, v246
	s_or_saveexec_b64 s[0:1], s[0:1]
	v_mov_b32_e32 v241, 0x100
	s_xor_b64 exec, exec, s[0:1]
	v_ashrrev_i32_e32 v246, 6, v245
	v_lshl_add_u32 v240, v246, 10, v239
	v_mov_b32_e32 v241, 0x400
	s_or_b64 exec, exec, s[0:1]
	v_and_b32_e32 v244, 63, v247
	v_and_b32_e32 v249, 63, v245
	v_lshlrev_b32_e32 v0, 7, v249
	v_lshlrev_b32_e32 v248, 1, v244
	v_or_b32_e32 v1, v0, v248
	v_readlane_b32 s0, v250, 26
	v_lshlrev_b32_e32 v1, 2, v1
	v_readlane_b32 s1, v250, 27
	v_and_b32_e32 v243, 15, v247
	v_and_b32_e32 v4, 48, v247
	v_cmp_lt_u32_e64 s[6:7], 31, v244
	v_lshl_add_u64 v[230:231], s[42:43], 0, v[4:5]
	v_mov_b32_e32 v2, 0
	global_load_dwordx2 v[228:229], v1, s[0:1]
	v_or_b32_e32 v1, v0, v243
	v_cmp_gt_u32_e64 s[0:1], 32, v244
	v_mov_b32_e32 v0, 0
	v_lshlrev_b32_e32 v232, 5, v1
	v_mov_b32_e32 v1, 0
	v_mov_b32_e32 v3, 0
	s_waitcnt vmcnt(1)
	v_mov_b32_e32 v8, v5
	v_mov_b32_e32 v9, v5
	v_mov_b32_e32 v10, v5
	v_mov_b32_e32 v11, v5
	v_mov_b32_e32 v12, v5
	v_mov_b32_e32 v13, v5
	v_mov_b32_e32 v14, v5
	v_mov_b32_e32 v15, v5
	v_mov_b32_e32 v16, v5
	v_mov_b32_e32 v17, v5
	v_mov_b32_e32 v18, v5
	v_mov_b32_e32 v19, v5
	v_mov_b32_e32 v20, v5
	v_mov_b32_e32 v21, v5
	v_mov_b32_e32 v22, v5
	v_mov_b32_e32 v23, v5
	v_mov_b32_e32 v24, v5
	v_mov_b32_e32 v25, v5
	v_mov_b32_e32 v26, v5
	v_mov_b32_e32 v27, v5
	v_mov_b32_e32 v28, v5
	v_mov_b32_e32 v29, v5
	v_mov_b32_e32 v30, v5
	v_mov_b32_e32 v31, v5
	v_mov_b32_e32 v32, v5
	v_mov_b32_e32 v33, v5
	v_mov_b32_e32 v34, v5
	v_mov_b32_e32 v35, v5
	v_mov_b32_e32 v36, v5
	v_mov_b32_e32 v37, v5
	v_mov_b32_e32 v38, v5
	v_mov_b32_e32 v39, v5
	s_and_saveexec_b64 s[8:9], s[0:1]
	v_mov_b32_e32 v233, v5
	v_lshl_add_u64 v[0:1], v[230:231], 0, v[232:233]
	global_load_dwordx4 v[8:11], v[0:1], off
	global_load_dwordx4 v[12:15], v[0:1], off offset:512
	global_load_dwordx4 v[16:19], v[0:1], off offset:1024
	global_load_dwordx4 v[20:23], v[0:1], off offset:1536
	global_load_dwordx4 v[24:27], v[0:1], off offset:2048
	global_load_dwordx4 v[28:31], v[0:1], off offset:2560
	global_load_dwordx4 v[32:35], v[0:1], off offset:3072
	global_load_dwordx4 v[36:39], v[0:1], off offset:3584
.LBB0_1280:
.LBB0_1281:
.LBB0_1282:
.LBB0_1283:
.LBB0_1284:
.LBB0_1285:
.LBB0_1286:
.LBB0_1287:
.LBB0_1288:
.LBB0_1289:
.LBB0_1290:
.LBB0_1291:
.LBB0_1292:
	s_or_b64 exec, exec, s[8:9]
	v_bfe_u32 v54, v247, 4, 2
	v_lshlrev_b32_e32 v0, 8, v243
	v_lshlrev_b32_e32 v2, 3, v54
	v_lshl_or_b32 v4, v249, 12, v0
	v_lshl_add_u64 v[0:1], s[38:39], 0, v[4:5]
	v_lshlrev_b32_e32 v4, 1, v2
	v_lshl_add_u64 v[6:7], v[0:1], 0, v[4:5]
	global_load_dwordx4 v[0:3], v[6:7], off
	global_load_dwordx4 v[40:43], v[6:7], off offset:64
	global_load_dwordx4 v[44:47], v[6:7], off offset:128
	global_load_dwordx4 v[48:51], v[6:7], off offset:192
	v_bfe_u32 v55, v245, 5, 1
	v_and_b32_e32 v62, 31, v245
	v_lshlrev_b32_e32 v7, 7, v246
	v_lshlrev_b32_e32 v52, 5, v55
	v_mov_b32_e32 v68, v5
	v_mov_b32_e32 v69, v5
	v_lshlrev_b32_e32 v6, 2, v248
	v_or3_b32 v60, v7, v52, v62
	s_and_saveexec_b64 s[8:9], s[4:5]
	s_cbranch_execz .LBB0_1294
	v_ashrrev_i32_e32 v61, 31, v60
	v_readlane_b32 s12, v251, 39
	v_lshlrev_b64 v[52:53], 9, v[60:61]
	v_readlane_b32 s18, v251, 45
	v_readlane_b32 s19, v251, 46
	v_mov_b32_e32 v7, v5
	v_readlane_b32 s13, v251, 40
	v_lshl_add_u64 v[52:53], s[18:19], 0, v[52:53]
	v_lshl_add_u64 v[52:53], v[52:53], 0, v[6:7]
	global_load_dwordx2 v[68:69], v[52:53], off
	v_readlane_b32 s14, v251, 41
	v_readlane_b32 s15, v251, 42
	v_readlane_b32 s16, v251, 43
	v_readlane_b32 s17, v251, 44
	v_readlane_b32 s20, v251, 47
	v_readlane_b32 s21, v251, 48
	v_readlane_b32 s22, v251, 49
	v_readlane_b32 s23, v251, 50
	v_readlane_b32 s24, v251, 51
	v_readlane_b32 s25, v251, 52
	v_readlane_b32 s26, v251, 53
	v_readlane_b32 s27, v251, 54

.LBB0_1557:
	s_andn2_b64 vcc, exec, s[0:1]
	s_cbranch_vccnz .LBB0_1169
	v_mov_b32_e32 v247, v234
	s_movk_i32 s0, 0x100
	v_ashrrev_i32_e32 v242, 6, v247
	v_lshl_add_u32 v245, s3, 2, v242
	v_cmp_gt_i32_e64 s[4:5], s0, v245
	s_movk_i32 s0, 0xff
	v_cmp_lt_i32_e32 vcc, s0, v245
	s_and_saveexec_b64 s[0:1], vcc
	s_xor_b64 s[0:1], exec, s[0:1]
	v_add_u32_e32 v0, 0xffffff00, v245
	v_lshrrev_b32_e32 v246, 6, v0
	v_lshlrev_b32_e32 v240, 8, v246
	s_or_saveexec_b64 s[0:1], s[0:1]
	v_mov_b32_e32 v241, 0x100
	s_xor_b64 exec, exec, s[0:1]
	v_ashrrev_i32_e32 v246, 6, v245
	v_lshl_add_u32 v240, v246, 10, v239
	v_mov_b32_e32 v241, 0x400
	s_or_b64 exec, exec, s[0:1]
	v_and_b32_e32 v244, 63, v247
	v_and_b32_e32 v249, 63, v245
	v_lshlrev_b32_e32 v0, 7, v249
	v_lshlrev_b32_e32 v248, 1, v244
	v_or_b32_e32 v1, v0, v248
	v_readlane_b32 s0, v250, 26
	v_lshlrev_b32_e32 v1, 2, v1
	v_readlane_b32 s1, v250, 27
	v_and_b32_e32 v243, 15, v247
	v_and_b32_e32 v4, 48, v247
	v_cmp_lt_u32_e64 s[6:7], 31, v244
	v_lshl_add_u64 v[230:231], s[42:43], 0, v[4:5]
	v_mov_b32_e32 v2, 0
	global_load_dwordx2 v[228:229], v1, s[0:1]
	v_or_b32_e32 v1, v0, v243
	v_cmp_gt_u32_e64 s[0:1], 32, v244
	v_mov_b32_e32 v0, 0
	v_lshlrev_b32_e32 v232, 5, v1
	v_mov_b32_e32 v1, 0
	v_mov_b32_e32 v3, 0
	s_waitcnt vmcnt(1)
	v_mov_b32_e32 v8, v5
	v_mov_b32_e32 v9, v5
	v_mov_b32_e32 v10, v5
	v_mov_b32_e32 v11, v5
	v_mov_b32_e32 v12, v5
	v_mov_b32_e32 v13, v5
	v_mov_b32_e32 v14, v5
	v_mov_b32_e32 v15, v5
	v_mov_b32_e32 v16, v5
	v_mov_b32_e32 v17, v5
	v_mov_b32_e32 v18, v5
	v_mov_b32_e32 v19, v5
	v_mov_b32_e32 v20, v5
	v_mov_b32_e32 v21, v5
	v_mov_b32_e32 v22, v5
	v_mov_b32_e32 v23, v5
	v_mov_b32_e32 v24, v5
	v_mov_b32_e32 v25, v5
	v_mov_b32_e32 v26, v5
	v_mov_b32_e32 v27, v5
	v_mov_b32_e32 v28, v5
	v_mov_b32_e32 v29, v5
	v_mov_b32_e32 v30, v5
	v_mov_b32_e32 v31, v5
	v_mov_b32_e32 v32, v5
	v_mov_b32_e32 v33, v5
	v_mov_b32_e32 v34, v5
	v_mov_b32_e32 v35, v5
	v_mov_b32_e32 v36, v5
	v_mov_b32_e32 v37, v5
	v_mov_b32_e32 v38, v5
	v_mov_b32_e32 v39, v5
	s_and_saveexec_b64 s[8:9], s[0:1]
	v_mov_b32_e32 v233, v5
	v_lshl_add_u64 v[0:1], v[230:231], 0, v[232:233]
	global_load_dwordx4 v[8:11], v[0:1], off
	global_load_dwordx4 v[12:15], v[0:1], off offset:512
	global_load_dwordx4 v[16:19], v[0:1], off offset:1024
	global_load_dwordx4 v[20:23], v[0:1], off offset:1536
	global_load_dwordx4 v[24:27], v[0:1], off offset:2048
	global_load_dwordx4 v[28:31], v[0:1], off offset:2560
	global_load_dwordx4 v[32:35], v[0:1], off offset:3072
	global_load_dwordx4 v[36:39], v[0:1], off offset:3584

.LBB0_3259:
	s_andn2_b64 vcc, exec, s[0:1]
	s_cbranch_vccnz .LBB0_3305
	v_mov_b32_e32 v247, v234
	s_lshl_b32 s0, s56, 2
	s_addk_i32 s0, 0xf400
	v_ashrrev_i32_e32 v243, 6, v247
	v_add_u32_e32 v245, s0, v243
	s_movk_i32 s0, 0x100
	v_cmp_gt_i32_e64 s[4:5], s0, v245
	s_movk_i32 s0, 0xff
	v_cmp_lt_i32_e32 vcc, s0, v245
	s_and_saveexec_b64 s[0:1], vcc
	s_xor_b64 s[0:1], exec, s[0:1]
	v_add_u32_e32 v0, 0xffffff00, v245
	v_lshrrev_b32_e32 v246, 6, v0
	v_lshlrev_b32_e32 v240, 8, v246
	s_or_saveexec_b64 s[0:1], s[0:1]
	v_mov_b32_e32 v241, 0x100
	s_xor_b64 exec, exec, s[0:1]
	v_ashrrev_i32_e32 v246, 6, v245
	v_lshl_add_u32 v240, v246, 10, v239
	v_mov_b32_e32 v241, 0x400
	s_or_b64 exec, exec, s[0:1]
	v_and_b32_e32 v244, 63, v247
	v_and_or_b32 v249, v245, 63, 64
	v_lshlrev_b32_e32 v0, 7, v249
	v_lshlrev_b32_e32 v248, 1, v244
	v_or_b32_e32 v1, v0, v248
	v_lshlrev_b32_e32 v1, 2, v1
	global_load_dwordx2 v[228:229], v1, s[40:41]
	v_and_b32_e32 v242, 15, v247
	v_or_b32_e32 v1, v0, v242
	v_and_b32_e32 v4, 48, v247
	v_cmp_lt_u32_e64 s[6:7], 31, v244
	v_cmp_gt_u32_e64 s[0:1], 32, v244
	v_lshl_add_u64 v[230:231], s[44:45], 0, v[4:5]
	v_mov_b32_e32 v0, 0
	v_lshlrev_b32_e32 v232, 5, v1
	v_mov_b32_e32 v1, 0
	v_mov_b32_e32 v2, 0
	v_mov_b32_e32 v3, 0
	s_waitcnt vmcnt(1)
	v_mov_b32_e32 v8, v5
	v_mov_b32_e32 v9, v5
	v_mov_b32_e32 v10, v5
	v_mov_b32_e32 v11, v5
	v_mov_b32_e32 v12, v5
	v_mov_b32_e32 v13, v5
	v_mov_b32_e32 v14, v5
	v_mov_b32_e32 v15, v5
	v_mov_b32_e32 v16, v5
	v_mov_b32_e32 v17, v5
	v_mov_b32_e32 v18, v5
	v_mov_b32_e32 v19, v5
	v_mov_b32_e32 v20, v5
	v_mov_b32_e32 v21, v5
	v_mov_b32_e32 v22, v5
	v_mov_b32_e32 v23, v5
	v_mov_b32_e32 v24, v5
	v_mov_b32_e32 v25, v5
	v_mov_b32_e32 v26, v5
	v_mov_b32_e32 v27, v5
	v_mov_b32_e32 v28, v5
	v_mov_b32_e32 v29, v5
	v_mov_b32_e32 v30, v5
	v_mov_b32_e32 v31, v5
	v_mov_b32_e32 v32, v5
	v_mov_b32_e32 v33, v5
	v_mov_b32_e32 v34, v5
	v_mov_b32_e32 v35, v5
	v_mov_b32_e32 v36, v5
	v_mov_b32_e32 v37, v5
	v_mov_b32_e32 v38, v5
	v_mov_b32_e32 v39, v5
	s_and_saveexec_b64 s[8:9], s[0:1]
	v_mov_b32_e32 v233, v5
	v_lshl_add_u64 v[0:1], v[230:231], 0, v[232:233]
	global_load_dwordx4 v[8:11], v[0:1], off
	global_load_dwordx4 v[12:15], v[0:1], off offset:512
	global_load_dwordx4 v[16:19], v[0:1], off offset:1024
	global_load_dwordx4 v[20:23], v[0:1], off offset:1536
	global_load_dwordx4 v[24:27], v[0:1], off offset:2048
	global_load_dwordx4 v[28:31], v[0:1], off offset:2560
	global_load_dwordx4 v[32:35], v[0:1], off offset:3072
	global_load_dwordx4 v[36:39], v[0:1], off offset:3584
.LBB0_3268:
.LBB0_3269:
.LBB0_3270:
.LBB0_3271:
.LBB0_3272:
.LBB0_3273:
.LBB0_3274:
.LBB0_3275:
.LBB0_3276:
.LBB0_3277:
.LBB0_3278:
.LBB0_3279:
.LBB0_3280:
	s_or_b64 exec, exec, s[8:9]
	v_bfe_u32 v54, v247, 4, 2
	v_lshlrev_b32_e32 v0, 8, v242
	v_lshlrev_b32_e32 v2, 3, v54
	v_lshl_or_b32 v4, v249, 12, v0
	v_lshl_add_u64 v[0:1], s[50:51], 0, v[4:5]
	v_lshlrev_b32_e32 v4, 1, v2
	v_lshl_add_u64 v[6:7], v[0:1], 0, v[4:5]
	global_load_dwordx4 v[0:3], v[6:7], off
	global_load_dwordx4 v[40:43], v[6:7], off offset:64
	global_load_dwordx4 v[44:47], v[6:7], off offset:128
	global_load_dwordx4 v[48:51], v[6:7], off offset:192
	v_bfe_u32 v55, v245, 5, 1
	v_lshlrev_b32_e32 v7, 5, v55
	v_and_b32_e32 v68, 31, v245
	v_mov_b32_e32 v66, v5
	v_mov_b32_e32 v67, v5
	v_lshlrev_b32_e32 v6, 2, v248
	v_lshl_or_b32 v69, v246, 7, v7
	s_and_saveexec_b64 s[8:9], s[4:5]
	s_cbranch_execz .LBB0_3282
	v_or3_b32 v52, v69, v68, 64
	v_ashrrev_i32_e32 v53, 31, v52
	v_readlane_b32 s12, v251, 39
	v_lshlrev_b64 v[52:53], 9, v[52:53]
	v_readlane_b32 s18, v251, 45
	v_readlane_b32 s19, v251, 46
	v_mov_b32_e32 v7, v5
	v_readlane_b32 s13, v251, 40
	v_lshl_add_u64 v[52:53], s[18:19], 0, v[52:53]
	v_lshl_add_u64 v[52:53], v[52:53], 0, v[6:7]
	global_load_dwordx2 v[66:67], v[52:53], off
	v_readlane_b32 s14, v251, 41
	v_readlane_b32 s15, v251, 42
	v_readlane_b32 s16, v251, 43
	v_readlane_b32 s17, v251, 44
	v_readlane_b32 s20, v251, 47
	v_readlane_b32 s21, v251, 48
	v_readlane_b32 s22, v251, 49
	v_readlane_b32 s23, v251, 50
	v_readlane_b32 s24, v251, 51
	v_readlane_b32 s25, v251, 52
	v_readlane_b32 s26, v251, 53
	v_readlane_b32 s27, v251, 54

.LBB0_3545:
	s_andn2_b64 vcc, exec, s[0:1]
	s_cbranch_vccnz .LBB0_3157
	v_mov_b32_e32 v247, v234
	s_movk_i32 s0, 0x100
	v_ashrrev_i32_e32 v243, 6, v247
	v_lshl_add_u32 v245, s56, 2, v243
	v_cmp_gt_i32_e64 s[4:5], s0, v245
	s_movk_i32 s0, 0xff
	v_cmp_lt_i32_e32 vcc, s0, v245
	s_and_saveexec_b64 s[0:1], vcc
	s_xor_b64 s[0:1], exec, s[0:1]
	v_add_u32_e32 v0, 0xffffff00, v245
	v_lshrrev_b32_e32 v246, 6, v0
	v_lshlrev_b32_e32 v240, 8, v246
	s_or_saveexec_b64 s[0:1], s[0:1]
	v_mov_b32_e32 v241, 0x100
	s_xor_b64 exec, exec, s[0:1]
	v_ashrrev_i32_e32 v246, 6, v245
	v_lshl_add_u32 v240, v246, 10, v239
	v_mov_b32_e32 v241, 0x400
	s_or_b64 exec, exec, s[0:1]
	v_and_b32_e32 v244, 63, v247
	v_and_or_b32 v249, v245, 63, 64
	v_lshlrev_b32_e32 v0, 7, v249
	v_lshlrev_b32_e32 v248, 1, v244
	v_or_b32_e32 v1, v0, v248
	v_lshlrev_b32_e32 v1, 2, v1
	global_load_dwordx2 v[228:229], v1, s[40:41]
	v_and_b32_e32 v242, 15, v247
	v_or_b32_e32 v1, v0, v242
	v_and_b32_e32 v4, 48, v247
	v_cmp_lt_u32_e64 s[6:7], 31, v244
	v_cmp_gt_u32_e64 s[0:1], 32, v244
	v_lshl_add_u64 v[230:231], s[44:45], 0, v[4:5]
	v_mov_b32_e32 v0, 0
	v_lshlrev_b32_e32 v232, 5, v1
	v_mov_b32_e32 v1, 0
	v_mov_b32_e32 v2, 0
	v_mov_b32_e32 v3, 0
	s_waitcnt vmcnt(1)
	v_mov_b32_e32 v8, v5
	v_mov_b32_e32 v9, v5
	v_mov_b32_e32 v10, v5
	v_mov_b32_e32 v11, v5
	v_mov_b32_e32 v12, v5
	v_mov_b32_e32 v13, v5
	v_mov_b32_e32 v14, v5
	v_mov_b32_e32 v15, v5
	v_mov_b32_e32 v16, v5
	v_mov_b32_e32 v17, v5
	v_mov_b32_e32 v18, v5
	v_mov_b32_e32 v19, v5
	v_mov_b32_e32 v20, v5
	v_mov_b32_e32 v21, v5
	v_mov_b32_e32 v22, v5
	v_mov_b32_e32 v23, v5
	v_mov_b32_e32 v24, v5
	v_mov_b32_e32 v25, v5
	v_mov_b32_e32 v26, v5
	v_mov_b32_e32 v27, v5
	v_mov_b32_e32 v28, v5
	v_mov_b32_e32 v29, v5
	v_mov_b32_e32 v30, v5
	v_mov_b32_e32 v31, v5
	v_mov_b32_e32 v32, v5
	v_mov_b32_e32 v33, v5
	v_mov_b32_e32 v34, v5
	v_mov_b32_e32 v35, v5
	v_mov_b32_e32 v36, v5
	v_mov_b32_e32 v37, v5
	v_mov_b32_e32 v38, v5
	v_mov_b32_e32 v39, v5
	s_and_saveexec_b64 s[8:9], s[0:1]
	v_mov_b32_e32 v233, v5
	v_lshl_add_u64 v[0:1], v[230:231], 0, v[232:233]
	global_load_dwordx4 v[8:11], v[0:1], off
	global_load_dwordx4 v[12:15], v[0:1], off offset:512
	global_load_dwordx4 v[16:19], v[0:1], off offset:1024
	global_load_dwordx4 v[20:23], v[0:1], off offset:1536
	global_load_dwordx4 v[24:27], v[0:1], off offset:2048
	global_load_dwordx4 v[28:31], v[0:1], off offset:2560
	global_load_dwordx4 v[32:35], v[0:1], off offset:3072
	global_load_dwordx4 v[36:39], v[0:1], off offset:3584
